# v64 + P3 epilogue stores: lanes permuted with ds_bpermute so that each quad of consecutive lanes writes 64 contiguous bytes of one row (was 4 different rows per quad)
# speedup vs baseline: 1.0156x; 1.0069x over previous
; __device__ __forceinline__ unsigned cvt_pk_bf16(float lo, float hi) { unsigned r; asm volatile("v_cvt_pk_bf16_f32 %0, %1, %2" : "=v"(r) : "v"(lo), "v"(hi)); return r; }
;     __device__ __forceinline__ void operator()(const f32x4 (&acc)[2][2][4][2], const Unit& u, int wr, int wc, int fr, int fq) const {
;         const int row0 = u.pm * BM + wr * 64 + fr, col0 = u.pn * BM + wc * 32 + 8 * fq;
;         unsigned long long sq[2][4];
; #pragma unroll
;         for (int ai = 0; ai < 2; ++ai)
; #pragma unroll
;             for (int m = 0; m < 4; ++m) sq[ai][m] = ssq[row0 + ai * HALF + m * 16];
; #pragma unroll
;         for (int ai = 0; ai < 2; ++ai)
; #pragma unroll
;             for (int m = 0; m < 4; ++m) {
;                 const int row = row0 + ai * HALF + m * 16; const float rs = rsqrtf((float)sq[ai][m] * (1.0f / FIXS) * (1.0f / (float)D) + EPS);
; #pragma unroll
;                 for (int bj = 0; bj < 2; ++bj) { const f32x4 v0 = acc[ai][bj][m][0] * rs, v1 = acc[ai][bj][m][1] * rs;
;                     u32x4 w; w.x = cvt_pk_bf16(v0[0], v0[1]); w.y = cvt_pk_bf16(v0[2], v0[3]); w.z = cvt_pk_bf16(v1[0], v1[1]); w.w = cvt_pk_bf16(v1[2], v1[3]);
;                     *(u32x4*)(O + (size_t)row * LDP + col0 + bj * HALF) = w; }
;             }
;     }
.LBB0_429:
	v_mbcnt_lo_u32_b32 v233, -1, 0
	v_mbcnt_hi_u32_b32 v233, -1, v233
	v_lshrrev_b32_e32 v232, 2, v233
	v_and_b32_e32 v233, 3, v233
	v_lshl_add_u32 v232, v233, 4, v232
	v_lshlrev_b32_e32 v232, 2, v232
	v_lshl_add_u32 v146, s20, 8, v158
	v_ashrrev_i32_e32 v147, 31, v146
	v_lshl_add_u64 v[148:149], v[146:147], 3, s[36:37]
	v_or_b32_e32 v150, 16, v146
	global_load_dwordx2 v[166:167], v[148:149], off
	v_ashrrev_i32_e32 v151, 31, v150
	v_or_b32_e32 v156, 32, v146
	v_lshl_add_u64 v[144:145], v[150:151], 3, s[36:37]
	v_ashrrev_i32_e32 v157, 31, v156
	v_lshl_add_u64 v[152:153], v[156:157], 3, s[36:37]
	global_load_dwordx2 v[168:169], v[144:145], off
	global_load_dwordx2 v[170:171], v[152:153], off
	v_or_b32_e32 v154, 48, v146
	v_lshl_add_u32 v152, s21, 8, v160
	v_ashrrev_i32_e32 v155, 31, v154
	v_mov_b64_e32 v[144:145], s[34:35]
	v_ashrrev_i32_e32 v153, 31, v152
	v_lshl_add_u64 v[176:177], v[154:155], 3, s[36:37]
	v_add_u32_e32 v180, 0x80, v146
	v_add_u32_e32 v181, 0x90, v146
	v_add_u32_e32 v165, 0xa0, v146
	v_add_u32_e32 v157, 0xb0, v146
	v_mad_i64_i32 v[172:173], s[4:5], v146, s59, v[144:145]
	v_lshlrev_b64 v[146:147], 1, v[152:153]
	v_mad_i64_i32 v[174:175], s[4:5], v150, s59, v[144:145]
	global_load_dwordx2 v[178:179], v[148:149], off offset:1024
	global_load_dwordx2 v[152:153], v[148:149], off offset:1152
	global_load_dwordx2 v[150:151], v[148:149], off offset:1280
	s_nop 0
	global_load_dwordx2 v[176:177], v[176:177], off
	s_nop 0
	global_load_dwordx2 v[148:149], v[148:149], off offset:1408
	v_lshl_add_u64 v[172:173], v[172:173], 0, v[146:147]
	v_lshl_add_u64 v[174:175], v[174:175], 0, v[146:147]
	s_waitcnt vmcnt(0)
	v_ffbh_u32_e32 v155, v167
	v_min_u32_e32 v155, 32, v155
	v_lshlrev_b64 v[166:167], v155, v[166:167]
	v_min_u32_e32 v166, 1, v166
	v_or_b32_e32 v166, v167, v166
	v_ffbh_u32_e32 v182, v169
	v_min_u32_e32 v182, 32, v182
	v_ffbh_u32_e32 v183, v171
	v_lshlrev_b64 v[168:169], v182, v[168:169]
	v_min_u32_e32 v183, 32, v183
	v_min_u32_e32 v167, 1, v168
	v_lshlrev_b64 v[170:171], v183, v[170:171]
	v_cvt_f32_u32_e32 v166, v166
	v_or_b32_e32 v167, v169, v167
	v_min_u32_e32 v168, 1, v170
	v_cvt_f32_u32_e32 v167, v167
	v_or_b32_e32 v168, v171, v168
	v_sub_u32_e32 v155, 32, v155
	v_cvt_f32_u32_e32 v168, v168
	v_sub_u32_e32 v182, 32, v182
	v_ldexp_f32 v155, v166, v155
	v_mul_f32_e32 v155, 0x33800000, v155
	v_ldexp_f32 v166, v167, v182
	v_sub_u32_e32 v183, 32, v183
	v_fmamk_f32 v155, v155, 0x39800000, v164
	v_mul_f32_e32 v166, 0x33800000, v166
	v_ldexp_f32 v167, v168, v183
	v_mul_f32_e32 v168, 0x4b800000, v155
	v_fmamk_f32 v166, v166, 0x39800000, v164
	v_cmp_gt_f32_e32 vcc, s58, v155
	v_cmp_gt_f32_e64 s[4:5], s58, v166
	v_mul_f32_e32 v171, 0x33800000, v167
	v_cndmask_b32_e32 v155, v155, v168, vcc
	v_mul_f32_e32 v168, 0x4b800000, v166
	v_rsq_f32_e32 v155, v155
	v_cndmask_b32_e64 v166, v166, v168, s[4:5]
	v_rsq_f32_e32 v170, v166
	v_mul_f32_e32 v166, 0x45800000, v155
	v_cndmask_b32_e32 v166, v155, v166, vcc
	v_mul_f32_e32 v155, 0x45800000, v170
	v_pk_mul_f32 v[122:123], v[122:123], v[166:167] op_sel_hi:[1,0]
	v_pk_mul_f32 v[120:121], v[120:121], v[166:167] op_sel_hi:[1,0]
	v_cndmask_b32_e64 v170, v170, v155, s[4:5]
	v_pk_mul_f32 v[126:127], v[126:127], v[166:167] op_sel_hi:[1,0]
	v_pk_mul_f32 v[124:125], v[124:125], v[166:167] op_sel_hi:[1,0]
	v_pk_mul_f32 v[110:111], v[110:111], v[166:167] op_sel_hi:[1,0]
	v_pk_mul_f32 v[108:109], v[108:109], v[166:167] op_sel_hi:[1,0]
	v_pk_mul_f32 v[168:169], v[106:107], v[166:167] op_sel_hi:[1,0]
	v_pk_mul_f32 v[166:167], v[104:105], v[166:167] op_sel_hi:[1,0]
	v_cvt_pk_bf16_f32 v104, v124, v125
	v_cvt_pk_bf16_f32 v105, v126, v127
	v_cvt_pk_bf16_f32 v106, v120, v121
	v_cvt_pk_bf16_f32 v107, v122, v123
	v_pk_mul_f32 v[120:121], v[98:99], v[170:171] op_sel_hi:[1,0]
	v_pk_mul_f32 v[122:123], v[96:97], v[170:171] op_sel_hi:[1,0]
	ds_bpermute_b32 v230, v232, v172
	ds_bpermute_b32 v231, v232, v173
	ds_bpermute_b32 v226, v232, v104
	ds_bpermute_b32 v227, v232, v105
	ds_bpermute_b32 v228, v232, v106
	ds_bpermute_b32 v229, v232, v107
	s_waitcnt lgkmcnt(0)
	global_store_dwordx4 v[230:231], v[226:229], off
	v_cvt_pk_bf16_f32 v96, v108, v109
	v_cvt_pk_bf16_f32 v97, v110, v111
	v_cvt_pk_bf16_f32 v98, v166, v167
	v_pk_mul_f32 v[118:119], v[118:119], v[170:171] op_sel_hi:[1,0]
	v_pk_mul_f32 v[116:117], v[116:117], v[170:171] op_sel_hi:[1,0]
	v_pk_mul_f32 v[112:113], v[112:113], v[170:171] op_sel_hi:[1,0]
	v_cvt_pk_bf16_f32 v99, v168, v169
	ds_bpermute_b32 v234, v232, v96
	ds_bpermute_b32 v235, v232, v97
	ds_bpermute_b32 v236, v232, v98
	ds_bpermute_b32 v237, v232, v99
	s_waitcnt lgkmcnt(0)
	global_store_dwordx4 v[230:231], v[234:237], off offset:256
	v_pk_mul_f32 v[114:115], v[114:115], v[170:171] op_sel_hi:[1,0]
	v_pk_mul_f32 v[100:101], v[100:101], v[170:171] op_sel_hi:[1,0]
	v_cvt_pk_bf16_f32 v96, v116, v117
	v_cvt_pk_bf16_f32 v97, v118, v119
	v_cvt_pk_bf16_f32 v98, v112, v113
	v_cvt_pk_bf16_f32 v99, v114, v115
	ds_bpermute_b32 v230, v232, v174
	ds_bpermute_b32 v231, v232, v175
	ds_bpermute_b32 v226, v232, v96
	ds_bpermute_b32 v227, v232, v97
	ds_bpermute_b32 v228, v232, v98
	ds_bpermute_b32 v229, v232, v99
	s_waitcnt lgkmcnt(0)
	global_store_dwordx4 v[230:231], v[226:229], off
	v_pk_mul_f32 v[102:103], v[102:103], v[170:171] op_sel_hi:[1,0]
	s_nop 0
	v_fmamk_f32 v98, v171, 0x39800000, v164
	v_mul_f32_e32 v99, 0x4b800000, v98
	v_cmp_gt_f32_e32 vcc, s58, v98
	v_cvt_pk_bf16_f32 v96, v100, v101
	v_cvt_pk_bf16_f32 v97, v102, v103
	s_nop 1
	v_cndmask_b32_e32 v98, v98, v99, vcc
	v_rsq_f32_e32 v100, v98
	v_cvt_pk_bf16_f32 v98, v122, v123
	v_cvt_pk_bf16_f32 v99, v120, v121
	ds_bpermute_b32 v234, v232, v96
	ds_bpermute_b32 v235, v232, v97
	ds_bpermute_b32 v236, v232, v98
	ds_bpermute_b32 v237, v232, v99
	s_waitcnt lgkmcnt(0)
; __device__ __forceinline__ unsigned cvt_pk_bf16(float lo, float hi) { unsigned r; asm volatile("v_cvt_pk_bf16_f32 %0, %1, %2" : "=v"(r) : "v"(lo), "v"(hi)); return r; }
;     __device__ __forceinline__ void operator()(const f32x4 (&acc)[2][2][4][2], const Unit& u, int wr, int wc, int fr, int fq) const {
;     ...
;         for (int ai = 0; ai < 2; ++ai)
; #pragma unroll
;             for (int m = 0; m < 4; ++m) {
;                 const int row = row0 + ai * HALF + m * 16; const float rs = rsqrtf((float)sq[ai][m] * (1.0f / FIXS) * (1.0f / (float)D) + EPS);
; #pragma unroll
;                 for (int bj = 0; bj < 2; ++bj) { const f32x4 v0 = acc[ai][bj][m][0] * rs, v1 = acc[ai][bj][m][1] * rs;
;                     u32x4 w; w.x = cvt_pk_bf16(v0[0], v0[1]); w.y = cvt_pk_bf16(v0[2], v0[3]); w.z = cvt_pk_bf16(v1[0], v1[1]); w.w = cvt_pk_bf16(v1[2], v1[3]);
;                     *(u32x4*)(O + (size_t)row * LDP + col0 + bj * HALF) = w; }
;             }
	global_store_dwordx4 v[230:231], v[234:237], off offset:256
	s_nop 1
	v_mul_f32_e32 v96, 0x45800000, v100
	v_cndmask_b32_e32 v96, v100, v96, vcc
	v_pk_mul_f32 v[92:93], v[92:93], v[96:97] op_sel_hi:[1,0]
	v_pk_mul_f32 v[98:99], v[90:91], v[96:97] op_sel_hi:[1,0]
	v_pk_mul_f32 v[90:91], v[88:89], v[96:97] op_sel_hi:[1,0]
	v_cvt_pk_bf16_f32 v88, v92, v93
	v_mad_i64_i32 v[92:93], s[4:5], v156, s59, v[144:145]
	v_pk_mul_f32 v[94:95], v[94:95], v[96:97] op_sel_hi:[1,0]
	v_lshl_add_u64 v[92:93], v[92:93], 0, v[146:147]
	v_cvt_pk_bf16_f32 v89, v94, v95
	v_cvt_pk_bf16_f32 v90, v90, v91
	v_cvt_pk_bf16_f32 v91, v98, v99
	ds_bpermute_b32 v230, v232, v92
	ds_bpermute_b32 v231, v232, v93
	ds_bpermute_b32 v226, v232, v88
	ds_bpermute_b32 v227, v232, v89
	ds_bpermute_b32 v228, v232, v90
	ds_bpermute_b32 v229, v232, v91
	s_waitcnt lgkmcnt(0)
	global_store_dwordx4 v[230:231], v[226:229], off
	v_pk_mul_f32 v[84:85], v[84:85], v[96:97] op_sel_hi:[1,0]
	v_pk_mul_f32 v[86:87], v[86:87], v[96:97] op_sel_hi:[1,0]
	v_pk_mul_f32 v[88:89], v[82:83], v[96:97] op_sel_hi:[1,0]
	v_pk_mul_f32 v[82:83], v[80:81], v[96:97] op_sel_hi:[1,0]
	v_ffbh_u32_e32 v80, v177
	v_min_u32_e32 v90, 32, v80
	v_lshlrev_b64 v[80:81], v90, v[176:177]
	v_min_u32_e32 v80, 1, v80
	v_or_b32_e32 v80, v81, v80
	v_cvt_f32_u32_e32 v91, v80
	v_cvt_pk_bf16_f32 v80, v84, v85
	v_sub_u32_e32 v84, 32, v90
	v_cvt_pk_bf16_f32 v81, v86, v87
	v_ldexp_f32 v84, v91, v84
	v_mul_f32_e32 v84, 0x33800000, v84
	v_fmamk_f32 v84, v84, 0x39800000, v164
	v_mul_f32_e32 v85, 0x4b800000, v84
	v_cmp_gt_f32_e32 vcc, s58, v84
	v_cvt_pk_bf16_f32 v82, v82, v83
	v_cvt_pk_bf16_f32 v83, v88, v89
	ds_bpermute_b32 v234, v232, v80
	ds_bpermute_b32 v235, v232, v81
	ds_bpermute_b32 v236, v232, v82
	ds_bpermute_b32 v237, v232, v83
	s_waitcnt lgkmcnt(0)
	global_store_dwordx4 v[230:231], v[234:237], off offset:256
	s_nop 0
	v_cndmask_b32_e32 v84, v84, v85, vcc
	v_rsq_f32_e32 v84, v84
	s_nop 0
	v_mul_f32_e32 v80, 0x45800000, v84
	v_cndmask_b32_e32 v80, v84, v80, vcc
	v_pk_mul_f32 v[76:77], v[76:77], v[80:81] op_sel_hi:[1,0]
	v_pk_mul_f32 v[82:83], v[74:75], v[80:81] op_sel_hi:[1,0]
	v_pk_mul_f32 v[74:75], v[72:73], v[80:81] op_sel_hi:[1,0]
	v_cvt_pk_bf16_f32 v72, v76, v77
	v_mad_i64_i32 v[76:77], s[4:5], v154, s59, v[144:145]
	v_pk_mul_f32 v[78:79], v[78:79], v[80:81] op_sel_hi:[1,0]
	v_lshl_add_u64 v[76:77], v[76:77], 0, v[146:147]
	v_cvt_pk_bf16_f32 v73, v78, v79
	v_cvt_pk_bf16_f32 v74, v74, v75
	v_cvt_pk_bf16_f32 v75, v82, v83
	ds_bpermute_b32 v230, v232, v76
	ds_bpermute_b32 v231, v232, v77
	ds_bpermute_b32 v226, v232, v72
	ds_bpermute_b32 v227, v232, v73
	ds_bpermute_b32 v228, v232, v74
	ds_bpermute_b32 v229, v232, v75
	s_waitcnt lgkmcnt(0)
	global_store_dwordx4 v[230:231], v[226:229], off
	v_pk_mul_f32 v[68:69], v[68:69], v[80:81] op_sel_hi:[1,0]
	v_pk_mul_f32 v[70:71], v[70:71], v[80:81] op_sel_hi:[1,0]
	v_pk_mul_f32 v[72:73], v[66:67], v[80:81] op_sel_hi:[1,0]
	v_pk_mul_f32 v[66:67], v[64:65], v[80:81] op_sel_hi:[1,0]
	v_ffbh_u32_e32 v64, v179
	v_min_u32_e32 v74, 32, v64
	v_lshlrev_b64 v[64:65], v74, v[178:179]
	v_min_u32_e32 v64, 1, v64
	v_or_b32_e32 v64, v65, v64
	v_cvt_f32_u32_e32 v75, v64
	v_cvt_pk_bf16_f32 v64, v68, v69
	v_sub_u32_e32 v68, 32, v74
	v_cvt_pk_bf16_f32 v65, v70, v71
	v_ldexp_f32 v68, v75, v68
	v_mul_f32_e32 v68, 0x33800000, v68
	v_fmamk_f32 v68, v68, 0x39800000, v164
	v_mul_f32_e32 v69, 0x4b800000, v68
	v_cmp_gt_f32_e32 vcc, s58, v68
	v_cvt_pk_bf16_f32 v66, v66, v67
	v_cvt_pk_bf16_f32 v67, v72, v73
	ds_bpermute_b32 v234, v232, v64
	ds_bpermute_b32 v235, v232, v65
	ds_bpermute_b32 v236, v232, v66
	ds_bpermute_b32 v237, v232, v67
	s_waitcnt lgkmcnt(0)
	global_store_dwordx4 v[230:231], v[234:237], off offset:256
	s_nop 0
	v_cndmask_b32_e32 v68, v68, v69, vcc
	v_rsq_f32_e32 v68, v68
	s_nop 0
	v_mul_f32_e32 v64, 0x45800000, v68
	v_cndmask_b32_e32 v64, v68, v64, vcc
	v_pk_mul_f32 v[60:61], v[60:61], v[64:65] op_sel_hi:[1,0]
	v_pk_mul_f32 v[66:67], v[58:59], v[64:65] op_sel_hi:[1,0]
	v_pk_mul_f32 v[58:59], v[56:57], v[64:65] op_sel_hi:[1,0]
	v_cvt_pk_bf16_f32 v56, v60, v61
	v_mad_i64_i32 v[60:61], s[4:5], v180, s59, v[144:145]
	v_pk_mul_f32 v[62:63], v[62:63], v[64:65] op_sel_hi:[1,0]
	v_lshl_add_u64 v[60:61], v[60:61], 0, v[146:147]
	v_cvt_pk_bf16_f32 v57, v62, v63
	v_cvt_pk_bf16_f32 v58, v58, v59
	v_cvt_pk_bf16_f32 v59, v66, v67
	ds_bpermute_b32 v230, v232, v60
	ds_bpermute_b32 v231, v232, v61
	ds_bpermute_b32 v226, v232, v56
	ds_bpermute_b32 v227, v232, v57
	ds_bpermute_b32 v228, v232, v58
	ds_bpermute_b32 v229, v232, v59
	s_waitcnt lgkmcnt(0)
	global_store_dwordx4 v[230:231], v[226:229], off
	v_pk_mul_f32 v[52:53], v[52:53], v[64:65] op_sel_hi:[1,0]
	v_pk_mul_f32 v[54:55], v[54:55], v[64:65] op_sel_hi:[1,0]
	v_pk_mul_f32 v[56:57], v[50:51], v[64:65] op_sel_hi:[1,0]
	v_pk_mul_f32 v[50:51], v[48:49], v[64:65] op_sel_hi:[1,0]
	v_ffbh_u32_e32 v48, v153
	v_min_u32_e32 v58, 32, v48
	v_lshlrev_b64 v[48:49], v58, v[152:153]
	v_min_u32_e32 v48, 1, v48
	v_or_b32_e32 v48, v49, v48
	v_cvt_f32_u32_e32 v59, v48
	v_cvt_pk_bf16_f32 v48, v52, v53
	v_sub_u32_e32 v52, 32, v58
	v_cvt_pk_bf16_f32 v49, v54, v55
	v_ldexp_f32 v52, v59, v52
	v_mul_f32_e32 v52, 0x33800000, v52
	v_fmamk_f32 v52, v52, 0x39800000, v164
	v_mul_f32_e32 v53, 0x4b800000, v52
	v_cmp_gt_f32_e32 vcc, s58, v52
	v_cvt_pk_bf16_f32 v50, v50, v51
	v_cvt_pk_bf16_f32 v51, v56, v57
	ds_bpermute_b32 v234, v232, v48
	ds_bpermute_b32 v235, v232, v49
	ds_bpermute_b32 v236, v232, v50
	ds_bpermute_b32 v237, v232, v51
	s_waitcnt lgkmcnt(0)
; __device__ __forceinline__ unsigned cvt_pk_bf16(float lo, float hi) { unsigned r; asm volatile("v_cvt_pk_bf16_f32 %0, %1, %2" : "=v"(r) : "v"(lo), "v"(hi)); return r; }
;     __device__ __forceinline__ void operator()(const f32x4 (&acc)[2][2][4][2], const Unit& u, int wr, int wc, int fr, int fq) const {
;     ...
;         for (int ai = 0; ai < 2; ++ai)
; #pragma unroll
;             for (int m = 0; m < 4; ++m) {
;                 const int row = row0 + ai * HALF + m * 16; const float rs = rsqrtf((float)sq[ai][m] * (1.0f / FIXS) * (1.0f / (float)D) + EPS);
; #pragma unroll
;                 for (int bj = 0; bj < 2; ++bj) { const f32x4 v0 = acc[ai][bj][m][0] * rs, v1 = acc[ai][bj][m][1] * rs;
;                     u32x4 w; w.x = cvt_pk_bf16(v0[0], v0[1]); w.y = cvt_pk_bf16(v0[2], v0[3]); w.z = cvt_pk_bf16(v1[0], v1[1]); w.w = cvt_pk_bf16(v1[2], v1[3]);
;                     *(u32x4*)(O + (size_t)row * LDP + col0 + bj * HALF) = w; }
;             }
; template <class Epi, class Sched, bool ALIGN_EPI = false, bool SP2 = false>
; __device__ __forceinline__ void gemm_phase(PG8_LAS unsigned char* lds, const Gemm g, const Sched& S, const Epi& E, int wid) {
;     ...
;         if constexpr (!Epi::AFTER_DRAIN) { E(acc, cur, wr, wc, fr, fq); S.done(cur); }
;         if (!has_next) break;
	global_store_dwordx4 v[230:231], v[234:237], off offset:256
	s_nop 0
	v_cndmask_b32_e32 v52, v52, v53, vcc
	v_rsq_f32_e32 v52, v52
	s_nop 0
	v_mul_f32_e32 v48, 0x45800000, v52
	v_cndmask_b32_e32 v48, v52, v48, vcc
	v_pk_mul_f32 v[44:45], v[44:45], v[48:49] op_sel_hi:[1,0]
	v_pk_mul_f32 v[50:51], v[42:43], v[48:49] op_sel_hi:[1,0]
	v_pk_mul_f32 v[42:43], v[40:41], v[48:49] op_sel_hi:[1,0]
	v_cvt_pk_bf16_f32 v40, v44, v45
	v_mad_i64_i32 v[44:45], s[4:5], v181, s59, v[144:145]
	v_pk_mul_f32 v[46:47], v[46:47], v[48:49] op_sel_hi:[1,0]
	v_lshl_add_u64 v[44:45], v[44:45], 0, v[146:147]
	v_cvt_pk_bf16_f32 v41, v46, v47
	v_cvt_pk_bf16_f32 v42, v42, v43
	v_cvt_pk_bf16_f32 v43, v50, v51
	ds_bpermute_b32 v230, v232, v44
	ds_bpermute_b32 v231, v232, v45
	ds_bpermute_b32 v226, v232, v40
	ds_bpermute_b32 v227, v232, v41
	ds_bpermute_b32 v228, v232, v42
	ds_bpermute_b32 v229, v232, v43
	s_waitcnt lgkmcnt(0)
	global_store_dwordx4 v[230:231], v[226:229], off
	v_pk_mul_f32 v[36:37], v[36:37], v[48:49] op_sel_hi:[1,0]
	v_pk_mul_f32 v[38:39], v[38:39], v[48:49] op_sel_hi:[1,0]
	v_pk_mul_f32 v[40:41], v[34:35], v[48:49] op_sel_hi:[1,0]
	v_pk_mul_f32 v[34:35], v[32:33], v[48:49] op_sel_hi:[1,0]
	v_ffbh_u32_e32 v32, v151
	v_min_u32_e32 v42, 32, v32
	v_lshlrev_b64 v[32:33], v42, v[150:151]
	v_min_u32_e32 v32, 1, v32
	v_or_b32_e32 v32, v33, v32
	v_cvt_f32_u32_e32 v43, v32
	v_cvt_pk_bf16_f32 v32, v36, v37
	v_sub_u32_e32 v36, 32, v42
	v_cvt_pk_bf16_f32 v33, v38, v39
	v_ldexp_f32 v36, v43, v36
	v_mul_f32_e32 v36, 0x33800000, v36
	v_fmamk_f32 v36, v36, 0x39800000, v164
	v_mul_f32_e32 v37, 0x4b800000, v36
	v_cmp_gt_f32_e32 vcc, s58, v36
	v_cvt_pk_bf16_f32 v34, v34, v35
	v_cvt_pk_bf16_f32 v35, v40, v41
	ds_bpermute_b32 v234, v232, v32
	ds_bpermute_b32 v235, v232, v33
	ds_bpermute_b32 v236, v232, v34
	ds_bpermute_b32 v237, v232, v35
	s_waitcnt lgkmcnt(0)
	global_store_dwordx4 v[230:231], v[234:237], off offset:256
	s_nop 0
	v_cndmask_b32_e32 v36, v36, v37, vcc
	v_rsq_f32_e32 v36, v36
	s_nop 0
	v_mul_f32_e32 v32, 0x45800000, v36
	v_cndmask_b32_e32 v32, v36, v32, vcc
	v_pk_mul_f32 v[28:29], v[28:29], v[32:33] op_sel_hi:[1,0]
	v_pk_mul_f32 v[34:35], v[26:27], v[32:33] op_sel_hi:[1,0]
	v_pk_mul_f32 v[26:27], v[24:25], v[32:33] op_sel_hi:[1,0]
	v_cvt_pk_bf16_f32 v24, v28, v29
	v_mad_i64_i32 v[28:29], s[4:5], v165, s59, v[144:145]
	v_pk_mul_f32 v[30:31], v[30:31], v[32:33] op_sel_hi:[1,0]
	v_lshl_add_u64 v[28:29], v[28:29], 0, v[146:147]
	v_cvt_pk_bf16_f32 v25, v30, v31
	v_cvt_pk_bf16_f32 v26, v26, v27
	v_cvt_pk_bf16_f32 v27, v34, v35
	ds_bpermute_b32 v230, v232, v28
	ds_bpermute_b32 v231, v232, v29
	ds_bpermute_b32 v226, v232, v24
	ds_bpermute_b32 v227, v232, v25
	ds_bpermute_b32 v228, v232, v26
	ds_bpermute_b32 v229, v232, v27
	s_waitcnt lgkmcnt(0)
	global_store_dwordx4 v[230:231], v[226:229], off
	v_pk_mul_f32 v[20:21], v[20:21], v[32:33] op_sel_hi:[1,0]
	v_pk_mul_f32 v[22:23], v[22:23], v[32:33] op_sel_hi:[1,0]
	v_pk_mul_f32 v[24:25], v[18:19], v[32:33] op_sel_hi:[1,0]
	v_pk_mul_f32 v[18:19], v[16:17], v[32:33] op_sel_hi:[1,0]
	v_ffbh_u32_e32 v16, v149
	v_min_u32_e32 v26, 32, v16
	v_lshlrev_b64 v[16:17], v26, v[148:149]
	v_min_u32_e32 v16, 1, v16
	v_or_b32_e32 v16, v17, v16
	v_cvt_f32_u32_e32 v27, v16
	v_cvt_pk_bf16_f32 v16, v20, v21
	v_sub_u32_e32 v20, 32, v26
	v_cvt_pk_bf16_f32 v17, v22, v23
	v_ldexp_f32 v20, v27, v20
	v_mul_f32_e32 v20, 0x33800000, v20
	v_fmamk_f32 v20, v20, 0x39800000, v164
	v_mul_f32_e32 v21, 0x4b800000, v20
	v_cmp_gt_f32_e32 vcc, s58, v20
	v_cvt_pk_bf16_f32 v18, v18, v19
	v_cvt_pk_bf16_f32 v19, v24, v25
	ds_bpermute_b32 v234, v232, v16
	ds_bpermute_b32 v235, v232, v17
	ds_bpermute_b32 v236, v232, v18
	ds_bpermute_b32 v237, v232, v19
	s_waitcnt lgkmcnt(0)
	global_store_dwordx4 v[230:231], v[234:237], off offset:256
	s_nop 0
	v_cndmask_b32_e32 v20, v20, v21, vcc
	v_rsq_f32_e32 v20, v20
	s_nop 0
	v_mul_f32_e32 v16, 0x45800000, v20
	v_cndmask_b32_e32 v16, v20, v16, vcc
	v_pk_mul_f32 v[12:13], v[12:13], v[16:17] op_sel_hi:[1,0]
	v_pk_mul_f32 v[18:19], v[10:11], v[16:17] op_sel_hi:[1,0]
	v_pk_mul_f32 v[10:11], v[8:9], v[16:17] op_sel_hi:[1,0]
	v_cvt_pk_bf16_f32 v8, v12, v13
	v_mad_i64_i32 v[12:13], s[4:5], v157, s59, v[144:145]
	v_pk_mul_f32 v[14:15], v[14:15], v[16:17] op_sel_hi:[1,0]
	v_lshl_add_u64 v[12:13], v[12:13], 0, v[146:147]
	v_cvt_pk_bf16_f32 v9, v14, v15
	v_cvt_pk_bf16_f32 v10, v10, v11
	v_cvt_pk_bf16_f32 v11, v18, v19
	ds_bpermute_b32 v230, v232, v12
	ds_bpermute_b32 v231, v232, v13
	ds_bpermute_b32 v226, v232, v8
	ds_bpermute_b32 v227, v232, v9
	ds_bpermute_b32 v228, v232, v10
	ds_bpermute_b32 v229, v232, v11
	s_waitcnt lgkmcnt(0)
	global_store_dwordx4 v[230:231], v[226:229], off
	s_and_b64 vcc, exec, s[2:3]
	s_mov_b64 s[2:3], -1
	v_pk_mul_f32 v[8:9], v[2:3], v[16:17] op_sel_hi:[1,0]
	v_pk_mul_f32 v[2:3], v[0:1], v[16:17] op_sel_hi:[1,0]
	v_pk_mul_f32 v[6:7], v[6:7], v[16:17] op_sel_hi:[1,0]
	v_pk_mul_f32 v[4:5], v[4:5], v[16:17] op_sel_hi:[1,0]
	s_nop 0
	v_cvt_pk_bf16_f32 v0, v4, v5
	v_cvt_pk_bf16_f32 v1, v6, v7
	v_cvt_pk_bf16_f32 v2, v2, v3
	v_cvt_pk_bf16_f32 v3, v8, v9
	ds_bpermute_b32 v234, v232, v0
	ds_bpermute_b32 v235, v232, v1
	ds_bpermute_b32 v236, v232, v2
	ds_bpermute_b32 v237, v232, v3
	s_waitcnt lgkmcnt(0)
	global_store_dwordx4 v[230:231], v[234:237], off offset:256
	s_cbranch_vccnz .LBB0_418
	s_andn2_b64 vcc, exec, s[6:7]
	s_cbranch_vccnz .LBB0_417
	s_barrier
	s_branch .LBB0_417
